# speedup vs baseline: 1.0398x; 1.0004x over previous
; __device__ __forceinline__ float rsq_(float x) { return __builtin_amdgcn_rsqf(x); }
; __device__ __forceinline__ void phase_resid(const Params& p, const float* __restrict__ gpost, float scale, const float* __restrict__ wdt) {
;     ...
;     if (wdt) {
; #pragma unroll
;       for (int r = 0; r < 2; ++r) {
;         const long row = row0 + r * (NTOK / 2);
;         float ss = 0.f, d[6] = {0.f, 0.f, 0.f, 0.f, 0.f, 0.f};
; #pragma unroll
;         for (int i = 0; i < 4; ++i) {
;           const int c = i * 256 + lane * 4;
;           const float4 x4 = xv[r][i];
;           ss += x4.x * x4.x + x4.y * x4.y + x4.z * x4.z + x4.w * x4.w;
; #pragma unroll
;           for (int h = 0; h < 6; ++h) {
;             const float4 w4 = *(const float4*)(wdt + h * DM + c);
;             d[h] += x4.x * w4.x + x4.y * w4.y + x4.z * w4.z + x4.w * w4.w;
;           }
;         }
;         ss = wave_sum(ss);
;         const float rsx = rsq_(ss * (1.f / DM) + EPS);
; #pragma unroll
;         for (int h = 0; h < 6; ++h) { const float v = wave_sum(d[h]); if (lane == h) L_dtbuf[row * 8 + h] = v * rsx; }
.LBB0_1059:
	s_or_b64 exec, exec, s[24:25]
	s_and_b64 vcc, exec, s[22:23]
	s_cbranch_vccz .LBB0_1054
	global_load_dwordx4 v[48:51], v[134:135], off
	global_load_dwordx4 v[200:203], v[136:137], off
	global_load_dwordx4 v[204:207], v[138:139], off
	global_load_dwordx4 v[208:211], v[140:141], off
	global_load_dwordx4 v[212:215], v[142:143], off
	global_load_dwordx4 v[216:219], v[144:145], off
	global_load_dwordx4 v[220:223], v[134:135], off offset:1024
	global_load_dwordx4 v[224:227], v[146:147], off
	global_load_dwordx4 v[228:231], v[148:149], off
	global_load_dwordx4 v[232:235], v[150:151], off
	global_load_dwordx4 v[236:239], v[152:153], off
	global_load_dwordx4 v[240:243], v[154:155], off
	global_load_dwordx4 v[244:247], v[134:135], off offset:2048
	ds_swizzle_b32 v181, v180 offset:swizzle(SWAP,1)
	s_waitcnt lgkmcnt(0)
	v_add_f32_e32 v180, v180, v181
	ds_swizzle_b32 v181, v180 offset:swizzle(SWAP,2)
	s_waitcnt lgkmcnt(0)
	v_add_f32_e32 v180, v180, v181
	ds_swizzle_b32 v181, v180 offset:swizzle(SWAP,4)
	s_waitcnt lgkmcnt(0)
	v_add_f32_e32 v180, v180, v181
	ds_swizzle_b32 v181, v180 offset:swizzle(SWAP,8)
	s_waitcnt lgkmcnt(0)
	v_add_f32_e32 v180, v180, v181
	ds_swizzle_b32 v181, v180 offset:swizzle(SWAP,16)
	s_waitcnt lgkmcnt(0)
	v_add_f32_e32 v180, v180, v181
	s_nop 0
	v_readlane_b32 s24, v180, 32
	v_readlane_b32 s8, v180, 0
	s_waitcnt vmcnt(0)
	v_mul_f32_e32 v49, v33, v49
	v_fmac_f32_e32 v49, v32, v48
	v_fmac_f32_e32 v49, v34, v50
	v_fmac_f32_e32 v49, v35, v51
	v_add_f32_e32 v60, 0, v49
	v_mov_b64_e32 v[96:97], v[200:201]
	v_mov_b64_e32 v[98:99], v[202:203]
	v_mov_b64_e32 v[80:81], v[204:205]
	v_mov_b64_e32 v[82:83], v[206:207]
	v_mov_b64_e32 v[68:69], v[208:209]
	v_mov_b64_e32 v[70:71], v[210:211]
	v_mov_b64_e32 v[56:57], v[212:213]
	v_mov_b64_e32 v[58:59], v[214:215]
	v_mov_b64_e32 v[48:49], v[216:217]
	v_mov_b64_e32 v[50:51], v[218:219]
	v_mov_b64_e32 v[52:53], v[220:221]
	v_mov_b64_e32 v[54:55], v[222:223]
	v_mov_b32_e32 v180, s24
	v_add_f32_e32 v180, s8, v180
	v_fmamk_f32 v180, v180, 0x3a800000, v183
	v_rsq_f32_e32 v192, v180
	v_lshlrev_b64 v[180:181], 5, v[128:129]
	v_lshl_add_u64 v[180:181], s[10:11], 0, v[180:181]
	s_waitcnt lgkmcnt(0)
	v_mul_f32_e32 v53, v37, v53
	v_fmac_f32_e32 v53, v36, v52
	v_fmac_f32_e32 v53, v38, v54
	v_fmac_f32_e32 v53, v39, v55
	v_add_f32_e32 v72, v60, v53
	v_mov_b64_e32 v[108:109], v[224:225]
	v_mov_b64_e32 v[110:111], v[226:227]
	v_mov_b64_e32 v[92:93], v[228:229]
	v_mov_b64_e32 v[94:95], v[230:231]
	v_mov_b64_e32 v[76:77], v[232:233]
	v_mov_b64_e32 v[78:79], v[234:235]
	v_mov_b64_e32 v[64:65], v[236:237]
	v_mov_b64_e32 v[66:67], v[238:239]
	v_mov_b64_e32 v[52:53], v[240:241]
	v_mov_b64_e32 v[54:55], v[242:243]
	v_mov_b64_e32 v[60:61], v[244:245]
	v_mov_b64_e32 v[62:63], v[246:247]
	s_waitcnt lgkmcnt(0)
	v_mul_f32_e32 v61, v41, v61
	v_fmac_f32_e32 v61, v40, v60
	v_fmac_f32_e32 v61, v42, v62
	v_fmac_f32_e32 v61, v43, v63
	v_add_f32_e32 v100, v72, v61
	global_load_dwordx4 v[116:119], v[156:157], off
	global_load_dwordx4 v[104:107], v[158:159], off
	global_load_dwordx4 v[88:91], v[160:161], off
	global_load_dwordx4 v[72:75], v[162:163], off
	global_load_dwordx4 v[60:63], v[164:165], off
	global_load_dwordx4 v[84:87], v[134:135], off offset:3072
	global_load_dwordx4 v[200:203], v[166:167], off
	global_load_dwordx4 v[204:207], v[168:169], off
	global_load_dwordx4 v[208:211], v[170:171], off
	global_load_dwordx4 v[212:215], v[174:175], off
	global_load_dwordx4 v[216:219], v[176:177], off
	s_waitcnt vmcnt(0) lgkmcnt(0)
	v_mul_f32_e32 v85, v45, v85
	v_fmac_f32_e32 v85, v44, v84
	v_fmac_f32_e32 v85, v46, v86
	v_fmac_f32_e32 v85, v47, v87
	v_add_f32_e32 v193, v100, v85
	v_mov_b64_e32 v[124:125], v[200:201]
	v_mov_b64_e32 v[126:127], v[202:203]
	v_mov_b64_e32 v[120:121], v[204:205]
	v_mov_b64_e32 v[122:123], v[206:207]
	v_mov_b64_e32 v[112:113], v[208:209]
	v_mov_b64_e32 v[114:115], v[210:211]
	v_mov_b64_e32 v[100:101], v[212:213]
	v_mov_b64_e32 v[102:103], v[214:215]
	v_mov_b64_e32 v[84:85], v[216:217]
	v_mov_b64_e32 v[86:87], v[218:219]
	v_mul_f32_e32 v97, v33, v97
	v_fmac_f32_e32 v97, v32, v96
	v_fmac_f32_e32 v97, v34, v98
	v_fmac_f32_e32 v97, v35, v99
	v_add_f32_e32 v96, 0, v97
	v_mul_f32_e32 v97, v37, v109
	v_fmac_f32_e32 v97, v36, v108
	v_fmac_f32_e32 v97, v38, v110
	v_fmac_f32_e32 v97, v39, v111
	v_add_f32_e32 v96, v96, v97
	v_mul_f32_e32 v97, v41, v117
	v_fmac_f32_e32 v97, v40, v116
	v_fmac_f32_e32 v97, v42, v118
	v_fmac_f32_e32 v97, v43, v119
	v_add_f32_e32 v96, v96, v97
	v_mul_f32_e32 v97, v45, v125
	v_fmac_f32_e32 v97, v44, v124
	v_fmac_f32_e32 v97, v46, v126
	v_fmac_f32_e32 v97, v47, v127
	v_add_f32_e32 v96, v96, v97
	v_mul_f32_e32 v81, v33, v81
	v_fmac_f32_e32 v81, v32, v80
	v_fmac_f32_e32 v81, v34, v82
	v_fmac_f32_e32 v81, v35, v83
	v_add_f32_e32 v80, 0, v81
	v_mul_f32_e32 v81, v37, v93
	v_fmac_f32_e32 v81, v36, v92
	v_fmac_f32_e32 v81, v38, v94
	v_fmac_f32_e32 v81, v39, v95
	v_add_f32_e32 v80, v80, v81
	v_mul_f32_e32 v81, v41, v105
	v_fmac_f32_e32 v81, v40, v104
	v_fmac_f32_e32 v81, v42, v106
	v_fmac_f32_e32 v81, v43, v107
	v_add_f32_e32 v80, v80, v81
	v_mul_f32_e32 v81, v45, v121
	v_fmac_f32_e32 v81, v44, v120
	v_fmac_f32_e32 v81, v46, v122
	v_fmac_f32_e32 v81, v47, v123
	v_add_f32_e32 v80, v80, v81
	v_mul_f32_e32 v69, v33, v69
	v_fmac_f32_e32 v69, v32, v68
	v_fmac_f32_e32 v69, v34, v70
	v_fmac_f32_e32 v69, v35, v71
	v_add_f32_e32 v68, 0, v69
	v_mul_f32_e32 v69, v37, v77
	v_fmac_f32_e32 v69, v36, v76
	v_fmac_f32_e32 v69, v38, v78
	v_fmac_f32_e32 v69, v39, v79
	v_add_f32_e32 v68, v68, v69
	v_mul_f32_e32 v69, v41, v89
	v_fmac_f32_e32 v69, v40, v88
	v_fmac_f32_e32 v69, v42, v90
	v_fmac_f32_e32 v69, v43, v91
; __device__ __forceinline__ float rsq_(float x) { return __builtin_amdgcn_rsqf(x); }
; __device__ __forceinline__ void phase_resid(const Params& p, const float* __restrict__ gpost, float scale, const float* __restrict__ wdt) {
;     ...
; #pragma unroll
;         for (int i = 0; i < 4; ++i) {
;           const int c = i * 256 + lane * 4;
;           const float4 x4 = xv[r][i];
;           ss += x4.x * x4.x + x4.y * x4.y + x4.z * x4.z + x4.w * x4.w;
; #pragma unroll
;           for (int h = 0; h < 6; ++h) {
;             const float4 w4 = *(const float4*)(wdt + h * DM + c);
;             d[h] += x4.x * w4.x + x4.y * w4.y + x4.z * w4.z + x4.w * w4.w;
;           }
;         }
;         ss = wave_sum(ss);
;         const float rsx = rsq_(ss * (1.f / DM) + EPS);
; #pragma unroll
;         for (int h = 0; h < 6; ++h) { const float v = wave_sum(d[h]); if (lane == h) L_dtbuf[row * 8 + h] = v * rsx; }
	v_add_f32_e32 v68, v68, v69
	v_mul_f32_e32 v69, v45, v113
	v_fmac_f32_e32 v69, v44, v112
	v_fmac_f32_e32 v69, v46, v114
	v_fmac_f32_e32 v69, v47, v115
	v_add_f32_e32 v68, v68, v69
	v_mul_f32_e32 v57, v33, v57
	v_fmac_f32_e32 v57, v32, v56
	v_fmac_f32_e32 v57, v34, v58
	v_fmac_f32_e32 v57, v35, v59
	v_add_f32_e32 v56, 0, v57
	v_mul_f32_e32 v57, v37, v65
	v_fmac_f32_e32 v57, v36, v64
	v_fmac_f32_e32 v57, v38, v66
	v_fmac_f32_e32 v57, v39, v67
	v_add_f32_e32 v56, v56, v57
	v_mul_f32_e32 v57, v41, v73
	v_fmac_f32_e32 v57, v40, v72
	v_fmac_f32_e32 v57, v42, v74
	v_fmac_f32_e32 v57, v43, v75
	v_add_f32_e32 v56, v56, v57
	v_mul_f32_e32 v57, v45, v101
	v_fmac_f32_e32 v57, v44, v100
	v_fmac_f32_e32 v57, v46, v102
	v_fmac_f32_e32 v57, v47, v103
	v_add_f32_e32 v56, v56, v57
	v_mul_f32_e32 v33, v33, v49
	v_fmac_f32_e32 v33, v32, v48
	v_fmac_f32_e32 v33, v34, v50
	v_fmac_f32_e32 v33, v35, v51
	v_add_f32_e32 v32, 0, v33
	v_mul_f32_e32 v33, v37, v53
	v_fmac_f32_e32 v33, v36, v52
	v_fmac_f32_e32 v33, v38, v54
	v_fmac_f32_e32 v33, v39, v55
	v_add_f32_e32 v32, v32, v33
	v_mul_f32_e32 v33, v41, v61
	v_fmac_f32_e32 v33, v40, v60
	v_fmac_f32_e32 v33, v42, v62
	v_fmac_f32_e32 v33, v43, v63
	v_add_f32_e32 v32, v32, v33
	v_mul_f32_e32 v33, v45, v85
	v_fmac_f32_e32 v33, v44, v84
	v_fmac_f32_e32 v33, v46, v86
	v_fmac_f32_e32 v33, v47, v87
	v_add_f32_e32 v32, v32, v33
	ds_swizzle_b32 v129, v193 offset:swizzle(SWAP,1)
	ds_swizzle_b32 v97, v96 offset:swizzle(SWAP,1)
	ds_swizzle_b32 v81, v80 offset:swizzle(SWAP,1)
	ds_swizzle_b32 v69, v68 offset:swizzle(SWAP,1)
	ds_swizzle_b32 v57, v56 offset:swizzle(SWAP,1)
	ds_swizzle_b32 v33, v32 offset:swizzle(SWAP,1)
	s_waitcnt lgkmcnt(0)
	v_add_f32_e32 v129, v193, v129
	v_add_f32_e32 v96, v96, v97
	v_add_f32_e32 v80, v80, v81
	v_add_f32_e32 v68, v68, v69
	v_add_f32_e32 v56, v56, v57
	v_add_f32_e32 v32, v32, v33
	ds_swizzle_b32 v193, v129 offset:swizzle(SWAP,2)
	ds_swizzle_b32 v97, v96 offset:swizzle(SWAP,2)
	ds_swizzle_b32 v81, v80 offset:swizzle(SWAP,2)
	ds_swizzle_b32 v69, v68 offset:swizzle(SWAP,2)
	ds_swizzle_b32 v57, v56 offset:swizzle(SWAP,2)
	ds_swizzle_b32 v33, v32 offset:swizzle(SWAP,2)
	s_waitcnt lgkmcnt(0)
	v_add_f32_e32 v129, v129, v193
	v_add_f32_e32 v96, v96, v97
	v_add_f32_e32 v80, v80, v81
	v_add_f32_e32 v68, v68, v69
	v_add_f32_e32 v56, v56, v57
	v_add_f32_e32 v32, v32, v33
	ds_swizzle_b32 v193, v129 offset:swizzle(SWAP,4)
	ds_swizzle_b32 v97, v96 offset:swizzle(SWAP,4)
	ds_swizzle_b32 v81, v80 offset:swizzle(SWAP,4)
	ds_swizzle_b32 v69, v68 offset:swizzle(SWAP,4)
	ds_swizzle_b32 v57, v56 offset:swizzle(SWAP,4)
	ds_swizzle_b32 v33, v32 offset:swizzle(SWAP,4)
	s_waitcnt lgkmcnt(0)
	v_add_f32_e32 v129, v129, v193
	v_add_f32_e32 v96, v96, v97
	v_add_f32_e32 v80, v80, v81
	v_add_f32_e32 v68, v68, v69
	v_add_f32_e32 v56, v56, v57
	v_add_f32_e32 v32, v32, v33
	ds_swizzle_b32 v193, v129 offset:swizzle(SWAP,8)
	ds_swizzle_b32 v97, v96 offset:swizzle(SWAP,8)
	ds_swizzle_b32 v81, v80 offset:swizzle(SWAP,8)
	ds_swizzle_b32 v69, v68 offset:swizzle(SWAP,8)
	ds_swizzle_b32 v57, v56 offset:swizzle(SWAP,8)
	ds_swizzle_b32 v33, v32 offset:swizzle(SWAP,8)
	s_waitcnt lgkmcnt(0)
	v_add_f32_e32 v129, v129, v193
	v_add_f32_e32 v96, v96, v97
	v_add_f32_e32 v80, v80, v81
	v_add_f32_e32 v68, v68, v69
	v_add_f32_e32 v56, v56, v57
	v_add_f32_e32 v32, v32, v33
	ds_swizzle_b32 v193, v129 offset:swizzle(SWAP,16)
	ds_swizzle_b32 v97, v96 offset:swizzle(SWAP,16)
	ds_swizzle_b32 v81, v80 offset:swizzle(SWAP,16)
	ds_swizzle_b32 v69, v68 offset:swizzle(SWAP,16)
	ds_swizzle_b32 v57, v56 offset:swizzle(SWAP,16)
	ds_swizzle_b32 v33, v32 offset:swizzle(SWAP,16)
	s_waitcnt lgkmcnt(0)
	v_add_f32_e32 v129, v129, v193
	v_add_f32_e32 v96, v96, v97
	v_add_f32_e32 v80, v80, v81
	v_add_f32_e32 v68, v68, v69
	v_add_f32_e32 v56, v56, v57
	v_add_f32_e32 v32, v32, v33
	s_nop 0
	v_readlane_b32 s8, v129, 0
	v_readlane_b32 s26, v129, 32
	s_and_saveexec_b64 s[24:25], s[0:1]
	s_cbranch_execz .LBB0_1062
	v_mov_b32_e32 v129, s26
	v_add_f32_e32 v129, s8, v129
	v_mul_f32_e32 v129, v192, v129
	global_store_dword v[180:181], v129, off
.LBB0_1062:
	s_or_b64 exec, exec, s[24:25]
	s_nop 0
	v_readlane_b32 s8, v96, 0
	v_readlane_b32 s26, v96, 32
	s_and_saveexec_b64 s[24:25], s[2:3]
	s_cbranch_execz .LBB0_1064
	v_mov_b32_e32 v96, s26
	v_add_f32_e32 v96, s8, v96
	v_mul_f32_e32 v96, v192, v96
	global_store_dword v[180:181], v96, off offset:4
.LBB0_1064:
	s_or_b64 exec, exec, s[24:25]
	s_nop 0
	v_readlane_b32 s8, v80, 0
	v_readlane_b32 s26, v80, 32
	s_and_saveexec_b64 s[24:25], s[4:5]
	s_cbranch_execz .LBB0_1066
	v_mov_b32_e32 v80, s26
	v_add_f32_e32 v80, s8, v80
	v_mul_f32_e32 v80, v192, v80
	global_store_dword v[180:181], v80, off offset:8
.LBB0_1066:
	s_or_b64 exec, exec, s[24:25]
	s_nop 0
	v_readlane_b32 s8, v68, 0
	v_readlane_b32 s26, v68, 32
	s_and_saveexec_b64 s[24:25], s[6:7]
	s_cbranch_execz .LBB0_1068
	v_mov_b32_e32 v68, s26
	v_add_f32_e32 v68, s8, v68
	v_mul_f32_e32 v68, v192, v68
	global_store_dword v[180:181], v68, off offset:12
.LBB0_1068:
	s_or_b64 exec, exec, s[24:25]
	s_nop 0
	v_readlane_b32 s8, v56, 0
	v_readlane_b32 s26, v56, 32
	s_and_saveexec_b64 s[24:25], s[12:13]
	s_cbranch_execz .LBB0_1070
	v_mov_b32_e32 v56, s26
	v_add_f32_e32 v56, s8, v56
	v_mul_f32_e32 v56, v192, v56
	global_store_dword v[180:181], v56, off offset:16
.LBB0_1070:
	s_or_b64 exec, exec, s[24:25]
	s_nop 0
	v_readlane_b32 s8, v32, 0
	v_readlane_b32 s26, v32, 32
	s_and_saveexec_b64 s[24:25], s[14:15]
	s_cbranch_execz .LBB0_1072
	v_mov_b32_e32 v32, s26
	v_add_f32_e32 v32, s8, v32
	v_mul_f32_e32 v32, v192, v32
	global_store_dword v[180:181], v32, off offset:20
; __device__ __forceinline__ float rsq_(float x) { return __builtin_amdgcn_rsqf(x); }
; __device__ __forceinline__ void phase_resid(const Params& p, const float* __restrict__ gpost, float scale, const float* __restrict__ wdt) {
;     ...
; #pragma unroll
;         for (int i = 0; i < 4; ++i) {
;           const int c = i * 256 + lane * 4;
;           const float4 x4 = xv[r][i];
;           ss += x4.x * x4.x + x4.y * x4.y + x4.z * x4.z + x4.w * x4.w;
; #pragma unroll
;           for (int h = 0; h < 6; ++h) {
;             const float4 w4 = *(const float4*)(wdt + h * DM + c);
;             d[h] += x4.x * w4.x + x4.y * w4.y + x4.z * w4.z + x4.w * w4.w;
;           }
;         }
;         ss = wave_sum(ss);
;         const float rsx = rsq_(ss * (1.f / DM) + EPS);
; #pragma unroll
;         for (int h = 0; h < 6; ++h) { const float v = wave_sum(d[h]); if (lane == h) L_dtbuf[row * 8 + h] = v * rsx; }
.LBB0_1072:
	s_or_b64 exec, exec, s[24:25]
	global_load_dwordx4 v[32:35], v[134:135], off
	global_load_dwordx4 v[200:203], v[136:137], off
	global_load_dwordx4 v[204:207], v[138:139], off
	global_load_dwordx4 v[208:211], v[140:141], off
	global_load_dwordx4 v[212:215], v[142:143], off
	global_load_dwordx4 v[216:219], v[144:145], off
	global_load_dwordx4 v[220:223], v[134:135], off offset:1024
	global_load_dwordx4 v[224:227], v[146:147], off
	global_load_dwordx4 v[228:231], v[148:149], off
	global_load_dwordx4 v[232:235], v[150:151], off
	global_load_dwordx4 v[236:239], v[152:153], off
	global_load_dwordx4 v[240:243], v[154:155], off
	global_load_dwordx4 v[244:247], v[134:135], off offset:2048
	ds_swizzle_b32 v112, v191 offset:swizzle(SWAP,1)
	s_waitcnt lgkmcnt(0)
	v_add_f32_e32 v112, v191, v112
	ds_swizzle_b32 v113, v112 offset:swizzle(SWAP,2)
	s_waitcnt lgkmcnt(0)
	v_add_f32_e32 v112, v112, v113
	ds_swizzle_b32 v113, v112 offset:swizzle(SWAP,4)
	s_waitcnt lgkmcnt(0)
	v_add_f32_e32 v112, v112, v113
	ds_swizzle_b32 v113, v112 offset:swizzle(SWAP,8)
	s_waitcnt lgkmcnt(0)
	v_add_f32_e32 v112, v112, v113
	ds_swizzle_b32 v113, v112 offset:swizzle(SWAP,16)
	s_waitcnt lgkmcnt(0)
	v_add_f32_e32 v112, v112, v113
	s_nop 0
	v_readlane_b32 s24, v112, 32
	v_readlane_b32 s8, v112, 0
	s_waitcnt vmcnt(0)
	v_mul_f32_e32 v33, v17, v33
	v_fmac_f32_e32 v33, v16, v32
	v_fmac_f32_e32 v33, v18, v34
	v_fmac_f32_e32 v33, v19, v35
	v_add_f32_e32 v44, 0, v33
	v_mov_b64_e32 v[80:81], v[200:201]
	v_mov_b64_e32 v[82:83], v[202:203]
	v_mov_b64_e32 v[64:65], v[204:205]
	v_mov_b64_e32 v[66:67], v[206:207]
	v_mov_b64_e32 v[52:53], v[208:209]
	v_mov_b64_e32 v[54:55], v[210:211]
	v_mov_b64_e32 v[40:41], v[212:213]
	v_mov_b64_e32 v[42:43], v[214:215]
	v_mov_b64_e32 v[32:33], v[216:217]
	v_mov_b64_e32 v[34:35], v[218:219]
	v_mov_b64_e32 v[36:37], v[220:221]
	v_mov_b64_e32 v[38:39], v[222:223]
	v_mov_b32_e32 v112, s24
	v_add_f32_e32 v112, s8, v112
	v_fmamk_f32 v112, v112, 0x3a800000, v183
	v_rsq_f32_e32 v114, v112
	v_lshlrev_b64 v[112:113], 5, v[178:179]
	v_lshl_add_u64 v[112:113], s[10:11], 0, v[112:113]
	s_waitcnt lgkmcnt(0)
	v_mul_f32_e32 v37, v21, v37
	v_fmac_f32_e32 v37, v20, v36
	v_fmac_f32_e32 v37, v22, v38
	v_fmac_f32_e32 v37, v23, v39
	v_add_f32_e32 v56, v44, v37
	v_mov_b64_e32 v[92:93], v[224:225]
	v_mov_b64_e32 v[94:95], v[226:227]
	v_mov_b64_e32 v[76:77], v[228:229]
	v_mov_b64_e32 v[78:79], v[230:231]
	v_mov_b64_e32 v[60:61], v[232:233]
	v_mov_b64_e32 v[62:63], v[234:235]
	v_mov_b64_e32 v[48:49], v[236:237]
	v_mov_b64_e32 v[50:51], v[238:239]
	v_mov_b64_e32 v[36:37], v[240:241]
	v_mov_b64_e32 v[38:39], v[242:243]
	v_mov_b64_e32 v[44:45], v[244:245]
	v_mov_b64_e32 v[46:47], v[246:247]
	s_waitcnt lgkmcnt(0)
	v_mul_f32_e32 v45, v25, v45
	v_fmac_f32_e32 v45, v24, v44
	v_fmac_f32_e32 v45, v26, v46
	v_fmac_f32_e32 v45, v27, v47
	v_add_f32_e32 v84, v56, v45
	global_load_dwordx4 v[100:103], v[156:157], off
	global_load_dwordx4 v[88:91], v[158:159], off
	global_load_dwordx4 v[72:75], v[160:161], off
	global_load_dwordx4 v[56:59], v[162:163], off
	global_load_dwordx4 v[44:47], v[164:165], off
	global_load_dwordx4 v[68:71], v[134:135], off offset:3072
	global_load_dwordx4 v[200:203], v[166:167], off
	global_load_dwordx4 v[204:207], v[168:169], off
	global_load_dwordx4 v[208:211], v[170:171], off
	global_load_dwordx4 v[212:215], v[174:175], off
	global_load_dwordx4 v[216:219], v[176:177], off
	s_waitcnt vmcnt(0) lgkmcnt(0)
	v_mul_f32_e32 v69, v29, v69
	v_fmac_f32_e32 v69, v28, v68
	v_fmac_f32_e32 v69, v30, v70
	v_fmac_f32_e32 v69, v31, v71
	v_add_f32_e32 v115, v84, v69
	v_mov_b64_e32 v[108:109], v[200:201]
	v_mov_b64_e32 v[110:111], v[202:203]
	v_mov_b64_e32 v[104:105], v[204:205]
	v_mov_b64_e32 v[106:107], v[206:207]
	v_mov_b64_e32 v[96:97], v[208:209]
	v_mov_b64_e32 v[98:99], v[210:211]
	v_mov_b64_e32 v[84:85], v[212:213]
	v_mov_b64_e32 v[86:87], v[214:215]
	v_mov_b64_e32 v[68:69], v[216:217]
	v_mov_b64_e32 v[70:71], v[218:219]
	v_mul_f32_e32 v81, v17, v81
	v_fmac_f32_e32 v81, v16, v80
	v_fmac_f32_e32 v81, v18, v82
	v_fmac_f32_e32 v81, v19, v83
	v_add_f32_e32 v80, 0, v81
	v_mul_f32_e32 v81, v21, v93
	v_fmac_f32_e32 v81, v20, v92
	v_fmac_f32_e32 v81, v22, v94
	v_fmac_f32_e32 v81, v23, v95
	v_add_f32_e32 v80, v80, v81
	v_mul_f32_e32 v81, v25, v101
	v_fmac_f32_e32 v81, v24, v100
	v_fmac_f32_e32 v81, v26, v102
	v_fmac_f32_e32 v81, v27, v103
	v_add_f32_e32 v80, v80, v81
	v_mul_f32_e32 v81, v29, v109
	v_fmac_f32_e32 v81, v28, v108
	v_fmac_f32_e32 v81, v30, v110
	v_fmac_f32_e32 v81, v31, v111
	v_add_f32_e32 v80, v80, v81
	v_mul_f32_e32 v65, v17, v65
	v_fmac_f32_e32 v65, v16, v64
	v_fmac_f32_e32 v65, v18, v66
	v_fmac_f32_e32 v65, v19, v67
	v_add_f32_e32 v64, 0, v65
	v_mul_f32_e32 v65, v21, v77
	v_fmac_f32_e32 v65, v20, v76
	v_fmac_f32_e32 v65, v22, v78
	v_fmac_f32_e32 v65, v23, v79
	v_add_f32_e32 v64, v64, v65
	v_mul_f32_e32 v65, v25, v89
	v_fmac_f32_e32 v65, v24, v88
	v_fmac_f32_e32 v65, v26, v90
	v_fmac_f32_e32 v65, v27, v91
	v_add_f32_e32 v64, v64, v65
	v_mul_f32_e32 v65, v29, v105
	v_fmac_f32_e32 v65, v28, v104
	v_fmac_f32_e32 v65, v30, v106
	v_fmac_f32_e32 v65, v31, v107
	v_add_f32_e32 v64, v64, v65
	v_mul_f32_e32 v53, v17, v53
	v_fmac_f32_e32 v53, v16, v52
	v_fmac_f32_e32 v53, v18, v54
	v_fmac_f32_e32 v53, v19, v55
	v_add_f32_e32 v52, 0, v53
	v_mul_f32_e32 v53, v21, v61
	v_fmac_f32_e32 v53, v20, v60
	v_fmac_f32_e32 v53, v22, v62
	v_fmac_f32_e32 v53, v23, v63
	v_add_f32_e32 v52, v52, v53
	v_mul_f32_e32 v53, v25, v73
	v_fmac_f32_e32 v53, v24, v72
	v_fmac_f32_e32 v53, v26, v74
	v_fmac_f32_e32 v53, v27, v75
	v_add_f32_e32 v52, v52, v53
; __device__ __forceinline__ float rsq_(float x) { return __builtin_amdgcn_rsqf(x); }
; __device__ __forceinline__ void phase_resid(const Params& p, const float* __restrict__ gpost, float scale, const float* __restrict__ wdt) {
;     ...
; #pragma unroll
;         for (int i = 0; i < 4; ++i) {
;           const int c = i * 256 + lane * 4;
;           const float4 x4 = xv[r][i];
;           ss += x4.x * x4.x + x4.y * x4.y + x4.z * x4.z + x4.w * x4.w;
; #pragma unroll
;           for (int h = 0; h < 6; ++h) {
;             const float4 w4 = *(const float4*)(wdt + h * DM + c);
;             d[h] += x4.x * w4.x + x4.y * w4.y + x4.z * w4.z + x4.w * w4.w;
;           }
;         }
;         ss = wave_sum(ss);
;         const float rsx = rsq_(ss * (1.f / DM) + EPS);
; #pragma unroll
;         for (int h = 0; h < 6; ++h) { const float v = wave_sum(d[h]); if (lane == h) L_dtbuf[row * 8 + h] = v * rsx; }
	v_mul_f32_e32 v53, v29, v97
	v_fmac_f32_e32 v53, v28, v96
	v_fmac_f32_e32 v53, v30, v98
	v_fmac_f32_e32 v53, v31, v99
	v_add_f32_e32 v52, v52, v53
	v_mul_f32_e32 v41, v17, v41
	v_fmac_f32_e32 v41, v16, v40
	v_fmac_f32_e32 v41, v18, v42
	v_fmac_f32_e32 v41, v19, v43
	v_add_f32_e32 v40, 0, v41
	v_mul_f32_e32 v41, v21, v49
	v_fmac_f32_e32 v41, v20, v48
	v_fmac_f32_e32 v41, v22, v50
	v_fmac_f32_e32 v41, v23, v51
	v_add_f32_e32 v40, v40, v41
	v_mul_f32_e32 v41, v25, v57
	v_fmac_f32_e32 v41, v24, v56
	v_fmac_f32_e32 v41, v26, v58
	v_fmac_f32_e32 v41, v27, v59
	v_add_f32_e32 v40, v40, v41
	v_mul_f32_e32 v41, v29, v85
	v_fmac_f32_e32 v41, v28, v84
	v_fmac_f32_e32 v41, v30, v86
	v_fmac_f32_e32 v41, v31, v87
	v_add_f32_e32 v40, v40, v41
	v_mul_f32_e32 v17, v17, v33
	v_fmac_f32_e32 v17, v16, v32
	v_fmac_f32_e32 v17, v18, v34
	v_fmac_f32_e32 v17, v19, v35
	v_add_f32_e32 v16, 0, v17
	v_mul_f32_e32 v17, v21, v37
	v_fmac_f32_e32 v17, v20, v36
	v_fmac_f32_e32 v17, v22, v38
	v_fmac_f32_e32 v17, v23, v39
	v_add_f32_e32 v16, v16, v17
	v_mul_f32_e32 v17, v25, v45
	v_fmac_f32_e32 v17, v24, v44
	v_fmac_f32_e32 v17, v26, v46
	v_fmac_f32_e32 v17, v27, v47
	v_add_f32_e32 v16, v16, v17
	v_mul_f32_e32 v17, v29, v69
	v_fmac_f32_e32 v17, v28, v68
	v_fmac_f32_e32 v17, v30, v70
	v_fmac_f32_e32 v17, v31, v71
	v_add_f32_e32 v16, v16, v17
	ds_swizzle_b32 v116, v115 offset:swizzle(SWAP,1)
	ds_swizzle_b32 v81, v80 offset:swizzle(SWAP,1)
	ds_swizzle_b32 v65, v64 offset:swizzle(SWAP,1)
	ds_swizzle_b32 v53, v52 offset:swizzle(SWAP,1)
	ds_swizzle_b32 v41, v40 offset:swizzle(SWAP,1)
	ds_swizzle_b32 v17, v16 offset:swizzle(SWAP,1)
	s_waitcnt lgkmcnt(0)
	v_add_f32_e32 v115, v115, v116
	v_add_f32_e32 v80, v80, v81
	v_add_f32_e32 v64, v64, v65
	v_add_f32_e32 v52, v52, v53
	v_add_f32_e32 v40, v40, v41
	v_add_f32_e32 v16, v16, v17
	ds_swizzle_b32 v116, v115 offset:swizzle(SWAP,2)
	ds_swizzle_b32 v81, v80 offset:swizzle(SWAP,2)
	ds_swizzle_b32 v65, v64 offset:swizzle(SWAP,2)
	ds_swizzle_b32 v53, v52 offset:swizzle(SWAP,2)
	ds_swizzle_b32 v41, v40 offset:swizzle(SWAP,2)
	ds_swizzle_b32 v17, v16 offset:swizzle(SWAP,2)
	s_waitcnt lgkmcnt(0)
	v_add_f32_e32 v115, v115, v116
	v_add_f32_e32 v80, v80, v81
	v_add_f32_e32 v64, v64, v65
	v_add_f32_e32 v52, v52, v53
	v_add_f32_e32 v40, v40, v41
	v_add_f32_e32 v16, v16, v17
	ds_swizzle_b32 v116, v115 offset:swizzle(SWAP,4)
	ds_swizzle_b32 v81, v80 offset:swizzle(SWAP,4)
	ds_swizzle_b32 v65, v64 offset:swizzle(SWAP,4)
	ds_swizzle_b32 v53, v52 offset:swizzle(SWAP,4)
	ds_swizzle_b32 v41, v40 offset:swizzle(SWAP,4)
	ds_swizzle_b32 v17, v16 offset:swizzle(SWAP,4)
	s_waitcnt lgkmcnt(0)
	v_add_f32_e32 v115, v115, v116
	v_add_f32_e32 v80, v80, v81
	v_add_f32_e32 v64, v64, v65
	v_add_f32_e32 v52, v52, v53
	v_add_f32_e32 v40, v40, v41
	v_add_f32_e32 v16, v16, v17
	ds_swizzle_b32 v116, v115 offset:swizzle(SWAP,8)
	ds_swizzle_b32 v81, v80 offset:swizzle(SWAP,8)
	ds_swizzle_b32 v65, v64 offset:swizzle(SWAP,8)
	ds_swizzle_b32 v53, v52 offset:swizzle(SWAP,8)
	ds_swizzle_b32 v41, v40 offset:swizzle(SWAP,8)
	ds_swizzle_b32 v17, v16 offset:swizzle(SWAP,8)
	s_waitcnt lgkmcnt(0)
	v_add_f32_e32 v115, v115, v116
	v_add_f32_e32 v80, v80, v81
	v_add_f32_e32 v64, v64, v65
	v_add_f32_e32 v52, v52, v53
	v_add_f32_e32 v40, v40, v41
	v_add_f32_e32 v16, v16, v17
	ds_swizzle_b32 v116, v115 offset:swizzle(SWAP,16)
	ds_swizzle_b32 v81, v80 offset:swizzle(SWAP,16)
	ds_swizzle_b32 v65, v64 offset:swizzle(SWAP,16)
	ds_swizzle_b32 v53, v52 offset:swizzle(SWAP,16)
	ds_swizzle_b32 v41, v40 offset:swizzle(SWAP,16)
	ds_swizzle_b32 v17, v16 offset:swizzle(SWAP,16)
	s_waitcnt lgkmcnt(0)
	v_add_f32_e32 v115, v115, v116
	v_add_f32_e32 v80, v80, v81
	v_add_f32_e32 v64, v64, v65
	v_add_f32_e32 v52, v52, v53
	v_add_f32_e32 v40, v40, v41
	v_add_f32_e32 v16, v16, v17
	s_nop 0
	v_readlane_b32 s8, v115, 0
	v_readlane_b32 s26, v115, 32
	s_and_saveexec_b64 s[24:25], s[0:1]
	s_cbranch_execz .LBB0_1074
	v_mov_b32_e32 v115, s26
	v_add_f32_e32 v115, s8, v115
	v_mul_f32_e32 v115, v114, v115
	global_store_dword v[112:113], v115, off
.LBB0_1074:
	s_or_b64 exec, exec, s[24:25]
	s_nop 0
	v_readlane_b32 s8, v80, 0
	v_readlane_b32 s26, v80, 32
	s_and_saveexec_b64 s[24:25], s[2:3]
	s_cbranch_execz .LBB0_1076
	v_mov_b32_e32 v80, s26
	v_add_f32_e32 v80, s8, v80
	v_mul_f32_e32 v80, v114, v80
	global_store_dword v[112:113], v80, off offset:4
.LBB0_1076:
	s_or_b64 exec, exec, s[24:25]
	s_nop 0
	v_readlane_b32 s8, v64, 0
	v_readlane_b32 s26, v64, 32
	s_and_saveexec_b64 s[24:25], s[4:5]
	s_cbranch_execz .LBB0_1078
	v_mov_b32_e32 v64, s26
	v_add_f32_e32 v64, s8, v64
	v_mul_f32_e32 v64, v114, v64
	global_store_dword v[112:113], v64, off offset:8
.LBB0_1078:
	s_or_b64 exec, exec, s[24:25]
	s_nop 0
	v_readlane_b32 s8, v52, 0
	v_readlane_b32 s26, v52, 32
	s_and_saveexec_b64 s[24:25], s[6:7]
	s_cbranch_execz .LBB0_1080
	v_mov_b32_e32 v52, s26
	v_add_f32_e32 v52, s8, v52
	v_mul_f32_e32 v52, v114, v52
	global_store_dword v[112:113], v52, off offset:12
.LBB0_1080:
	s_or_b64 exec, exec, s[24:25]
	s_nop 0
	v_readlane_b32 s8, v40, 0
	v_readlane_b32 s26, v40, 32
	s_and_saveexec_b64 s[24:25], s[12:13]
	s_cbranch_execz .LBB0_1082
	v_mov_b32_e32 v40, s26
	v_add_f32_e32 v40, s8, v40
	v_mul_f32_e32 v40, v114, v40
	global_store_dword v[112:113], v40, off offset:16
.LBB0_1082:
	s_or_b64 exec, exec, s[24:25]
	s_nop 0
	v_readlane_b32 s8, v16, 0
	v_readlane_b32 s26, v16, 32
	s_and_saveexec_b64 s[24:25], s[14:15]
	s_cbranch_execz .LBB0_1053
	v_mov_b32_e32 v16, s26
	v_add_f32_e32 v16, s8, v16
	v_mul_f32_e32 v16, v114, v16
	global_store_dword v[112:113], v16, off offset:20
	s_branch .LBB0_1053
